# direct HBM->LDS loads (strategy 5): attention loop K tiles via global_load_lds_dwordx4 issued in the first segment (source-side XOR swizzle), V tiles still register-staged
# speedup vs baseline: 1.0033x; 1.0033x over previous
; #define SBAR() __builtin_amdgcn_sched_barrier(0)
; #define VMW() asm volatile("s_waitcnt vmcnt(0)" ::: "memory")
; #define SWRITE_H(bf) do { *(LAS bf16x8*)(V_lds + (bf) * SHM_V + vst0) = st_v0; *(LAS bf16x8*)(V_lds + (bf) * SHM_V + vst1) = st_v1; \
;                           *(LAS bf16x8*)(K_lds + (bf) * SHM_K + kws) = st_k0; *(LAS bf16x8*)(K_lds + (bf) * SHM_K + kws + 32 * 256) = st_k1; } while (0)
; #define MASKT(P0_, P1_, t) do { const int kb_ = KBASE(t); bias_tile(P0_, P1_, Cs + kb_); if (kb_ + KVBLK - 1 > qlo) mask_tile(P0_, P1_, qm - kb_); } while (0)
; __device__ __forceinline__ void partialSM(f32x16& p0, f32x16& p1, float& m_reg, float& alpha) {
;     float pmax = p0[0];
; #pragma unroll
;     for (int r = 1; r < 16; ++r) pmax = fmaxf(pmax, p0[r]);
; #pragma unroll
;     for (int r = 0; r < 16; ++r) pmax = fmaxf(pmax, p1[r]);
;     { auto rr = __builtin_amdgcn_permlane32_swap(__float_as_uint(pmax), __float_as_uint(pmax), false, false);
;       pmax = fmaxf(__uint_as_float(rr[0]), __uint_as_float(rr[1])); }
;     float mn;
;     if (__builtin_expect(__all(pmax - m_reg <= THR2), 1)) { mn = m_reg; alpha = 1.f; }
;     else { mn = fmaxf(m_reg, pmax); alpha = __builtin_amdgcn_exp2f(m_reg - mn); m_reg = mn; }
; #pragma unroll
;     for (int r = 0; r < 16; ++r) p0[r] = p0[r] - mn;
; #pragma unroll
;     for (int r = 0; r < 16; ++r) p1[r] = p1[r] - mn;
; #pragma unroll
;     for (int r = 0; r < 16; ++r) p0[r] = __builtin_amdgcn_exp2f(p0[r]);
; }
; __device__ __forceinline__ void block(const BlockRef& cur, const int j0, const int NT, const int split, const SplitRef sp, lptr lds, int tid) {
;     ...
;     f32x16 pA0, pA1, pB0, pB1; float alA, alB; bf16x8 pa0, pa1, pa2, pa3;
;     SBAR(); qkt<0>(pA0, pA1, K_lds, r32, hi, qr);
;     MASKT(pA0, pA1, 0); partialSM(pA0, pA1, m_reg, alA);
;     VMW(); SWRITE_H(1);
;     __syncthreads();
.LBB0_863:
	v_lshlrev_b32_e32 v51, 3, v216
	v_and_b32_e32 v1, 0xc0, v1
	v_lshlrev_b32_e32 v52, 1, v216
	v_and_or_b32 v1, v51, 24, v1
	v_and_b32_e32 v52, 32, v52
	v_and_b32_e32 v51, 0x100, v51
	v_or3_b32 v1, v1, v52, v51
	v_add_u32_e32 v181, 0, v1
	v_max_f32_e32 v1, v19, v19
	v_max_f32_e32 v51, v18, v18
	v_max_f32_e32 v1, v51, v1
	v_max3_f32 v1, v1, v20, v21
	v_max3_f32 v1, v1, v22, v23
	v_max3_f32 v1, v1, v24, v25
	v_max3_f32 v1, v1, v26, v27
	v_max3_f32 v1, v1, v28, v29
	v_max3_f32 v1, v1, v30, v31
	v_max3_f32 v1, v1, v32, v33
	v_max3_f32 v1, v1, v2, v3
	v_max3_f32 v1, v1, v4, v5
	v_max3_f32 v1, v1, v6, v7
	v_max3_f32 v1, v1, v8, v9
	v_max3_f32 v1, v1, v10, v11
	v_max3_f32 v1, v1, v12, v13
	v_max3_f32 v1, v1, v14, v15
	s_sub_i32 s10, s1, s81
	v_max3_f32 v1, v1, v16, v17
	s_and_b64 s[8:9], s[6:7], exec
	v_mov_b32_e32 v51, v1
	s_cselect_b32 s10, s81, s10
	s_and_b64 s[8:9], s[90:91], exec
	v_permlane32_swap_b32_e32 v1, v51
	s_cselect_b32 s81, s10, s1
	s_and_b32 s1, s85, 0x3fffffc0
	v_max_f32_e32 v51, v51, v51
	v_max_f32_e32 v1, v1, v1
	s_lshl_b32 s1, s1, 2
	v_max_f32_e32 v1, v1, v51
	s_add_i32 s1, s1, 0
	v_add_f32_e32 v51, 0x7149f2ca, v1
	s_add_i32 s1, s1, 0x10000
	v_cmp_ge_f32_e32 vcc, s84, v51
	s_cmp_eq_u64 vcc, exec
	v_max_f32_e32 v1, 0xf149f2ca, v1
	s_cselect_b64 vcc, -1, 0
	v_mov_b32_e32 v52, 0xf149f2ca
	v_sub_f32_e32 v51, 0xf149f2ca, v1
	v_cndmask_b32_e32 v220, v1, v52, vcc
	v_exp_f32_e32 v51, v51
	v_sub_f32_e32 v1, v18, v220
	v_sub_f32_e32 v18, v19, v220
	v_sub_f32_e32 v19, v20, v220
	v_sub_f32_e32 v20, v21, v220
	v_sub_f32_e32 v21, v22, v220
	v_sub_f32_e32 v22, v23, v220
	v_sub_f32_e32 v23, v24, v220
	v_sub_f32_e32 v24, v25, v220
	v_sub_f32_e32 v25, v26, v220
	v_sub_f32_e32 v26, v27, v220
	v_sub_f32_e32 v27, v28, v220
	v_sub_f32_e32 v28, v29, v220
	v_sub_f32_e32 v29, v30, v220
	v_sub_f32_e32 v30, v31, v220
	v_sub_f32_e32 v31, v32, v220
	v_sub_f32_e32 v32, v33, v220
	v_exp_f32_e32 v160, v1
	v_exp_f32_e32 v227, v18
	v_exp_f32_e32 v158, v19
	v_exp_f32_e32 v161, v20
	v_exp_f32_e32 v157, v21
	v_exp_f32_e32 v159, v22
	v_exp_f32_e32 v155, v23
	v_exp_f32_e32 v156, v24
	v_exp_f32_e32 v152, v25
	v_exp_f32_e32 v154, v26
	v_exp_f32_e32 v151, v27
	v_exp_f32_e32 v153, v28
	v_exp_f32_e32 v148, v29
	v_exp_f32_e32 v150, v30
	v_exp_f32_e32 v147, v31
	v_exp_f32_e32 v149, v32
	s_waitcnt vmcnt(0)
	v_cndmask_b32_e64 v191, v51, 1.0, vcc
	v_sub_f32_e32 v67, v17, v220
	v_sub_f32_e32 v66, v16, v220
	v_sub_f32_e32 v69, v15, v220
	v_sub_f32_e32 v68, v14, v220
	v_sub_f32_e32 v71, v13, v220
	v_sub_f32_e32 v70, v12, v220
	v_sub_f32_e32 v73, v11, v220
	v_sub_f32_e32 v72, v10, v220
	v_sub_f32_e32 v75, v9, v220
	v_sub_f32_e32 v74, v8, v220
	v_sub_f32_e32 v77, v7, v220
	v_sub_f32_e32 v76, v6, v220
	v_sub_f32_e32 v79, v5, v220
	v_sub_f32_e32 v78, v4, v220
	s_cmp_lt_i32 s81, 3
	v_cmp_gt_u32_e64 s[8:9], 32, v216
	v_lshl_add_u32 v218, v175, 2, s1
	v_sub_f32_e32 v1, v3, v220
	v_sub_f32_e32 v80, v2, v220
	v_mov_b32_e32 v17, 0
	s_waitcnt vmcnt(3)
	ds_write_b128 v188, v[34:37] offset:16384
	s_waitcnt vmcnt(1)
	ds_write_b128 v189, v[38:41] offset:16384
	ds_write_b128 v190, v[42:45] offset:49152
	s_waitcnt vmcnt(0)
	ds_write_b128 v190, v[46:49] offset:57344
	s_waitcnt lgkmcnt(0)
	s_barrier
	s_cbranch_scc1 .LBB0_883
	s_add_i32 s10, s80, 0xffffff80
	v_add_u32_e32 v2, s10, v219
	s_lshr_b32 s11, s89, 1
	v_sub_u32_e32 v2, v2, v175
	s_lshl_b32 s10, s92, 6
	s_lshl_b32 s12, s11, 7
	v_subrev_u32_e32 v2, s10, v2
	s_add_i32 s10, s12, s10
	s_add_i32 s89, s10, 0x7f
	s_lshl_b32 s10, s11, 9
	s_lshl_b32 s11, s92, 8
	s_add_i32 s10, s10, s11
	s_add_i32 s10, s10, 0
	s_add_i32 s10, s10, 0x10900
	v_mov_b32_e32 v51, v163
	v_add_u32_e32 v223, s10, v162
	v_mov_b32_e32 v162, 0
	v_lshl_add_u64 v[176:177], s[40:41], 0, v[50:51]
	v_lshl_add_u64 v[178:179], s[72:73], 0, v[50:51]
	v_and_b32_e32 v212, 0x70, v174
	v_xor_b32_e32 v212, v178, v212
	v_mov_b32_e32 v213, v179
	v_lshrrev_b32_e32 v210, 6, v174
	v_and_b32_e32 v210, 7, v210
	v_lshlrev_b32_e32 v211, 10, v210
	s_nop 1
	v_readfirstlane_b32 s32, v211
	s_mov_b32 s88, 2
	v_lshl_add_u32 v221, v219, 2, s1
	v_subrev_u32_e32 v222, s12, v2
	v_mov_b32_e32 v50, 0
	v_mov_b32_e32 v51, v162
	v_mov_b32_e32 v52, v162
	v_mov_b32_e32 v53, v162
	v_mov_b32_e32 v54, v162
	v_mov_b32_e32 v55, v162
	v_mov_b32_e32 v56, v162
	v_mov_b32_e32 v57, v162
	v_mov_b32_e32 v58, v162
	v_mov_b32_e32 v59, v162
	v_mov_b32_e32 v60, v162
	v_mov_b32_e32 v61, v162
	v_mov_b32_e32 v62, v162
	v_mov_b32_e32 v63, v162
	v_mov_b32_e32 v64, v162
	v_mov_b32_e32 v65, v162
	v_mov_b32_e32 v34, 0
	v_mov_b32_e32 v35, v162
	v_mov_b32_e32 v36, v162
	v_mov_b32_e32 v37, v162
	v_mov_b32_e32 v38, v162
	v_mov_b32_e32 v39, v162
	v_mov_b32_e32 v40, v162
	v_mov_b32_e32 v41, v162
	v_mov_b32_e32 v42, v162
	v_mov_b32_e32 v43, v162
	v_mov_b32_e32 v44, v162
	v_mov_b32_e32 v45, v162
	v_mov_b32_e32 v46, v162
	v_mov_b32_e32 v47, v162
	v_mov_b32_e32 v48, v162
	v_mov_b32_e32 v49, v162
	v_mov_b32_e32 v18, 0
	v_mov_b32_e32 v19, v162
	v_mov_b32_e32 v20, v162
	v_mov_b32_e32 v21, v162
	v_mov_b32_e32 v22, v162
	v_mov_b32_e32 v23, v162
	v_mov_b32_e32 v24, v162
	v_mov_b32_e32 v25, v162
	v_mov_b32_e32 v26, v162
	v_mov_b32_e32 v27, v162
	v_mov_b32_e32 v28, v162
	v_mov_b32_e32 v29, v162
	v_mov_b32_e32 v30, v162
	v_mov_b32_e32 v31, v162
	v_mov_b32_e32 v32, v162
	v_mov_b32_e32 v33, v162
	v_mov_b32_e32 v2, 0
	v_mov_b32_e32 v3, v162
	v_mov_b32_e32 v4, v162
	v_mov_b32_e32 v5, v162
	v_mov_b32_e32 v6, v162
	v_mov_b32_e32 v7, v162
	v_mov_b32_e32 v8, v162
	v_mov_b32_e32 v9, v162
	v_mov_b32_e32 v10, v162
	v_mov_b32_e32 v11, v162
	v_mov_b32_e32 v12, v162
	v_mov_b32_e32 v13, v162
	v_mov_b32_e32 v14, v162
	v_mov_b32_e32 v15, v162
	v_mov_b32_e32 v16, v162
	v_mov_b32_e32 v17, v162
	s_mov_b32 s92, 0x90000
.LBB0_865:
	ds_read_b128 v[82:85], v187 offset:49152
	ds_read_b128 v[86:89], v187 offset:57344
	ds_read_b128 v[236:239], v185 offset:49152
	ds_read_b128 v[240:243], v185 offset:57344
	s_waitcnt lgkmcnt(3)
	v_mfma_f32_32x32x16_bf16 v[98:113], v[82:85], v[142:145], 0
	v_exp_f32_e32 v80, v80
	v_exp_f32_e32 v1, v1
	v_exp_f32_e32 v78, v78
	s_waitcnt lgkmcnt(2)
	v_mfma_f32_32x32x16_bf16 v[82:97], v[86:89], v[142:145], 0
	v_exp_f32_e32 v79, v79
	v_exp_f32_e32 v76, v76
	v_exp_f32_e32 v77, v77
	s_waitcnt lgkmcnt(0)
	v_mfma_f32_32x32x16_bf16 v[82:97], v[240:243], v[138:141], v[82:97]
	v_exp_f32_e32 v81, v74
	v_exp_f32_e32 v146, v75
	v_exp_f32_e32 v226, v72
	v_mfma_f32_32x32x16_bf16 v[98:113], v[236:239], v[138:141], v[98:113]
	v_exp_f32_e32 v233, v66
	v_add_f32_e32 v66, 0, v160
	v_add_f32_e32 v66, v227, v66
	v_add_f32_e32 v66, v158, v66
	v_add_f32_e32 v66, v161, v66
	ds_read_b128 v[236:239], v184 offset:49152
	ds_read_b128 v[240:243], v184 offset:57344
	s_waitcnt lgkmcnt(0)
	v_mfma_f32_32x32x16_bf16 v[82:97], v[240:243], v[134:137], v[82:97]
	v_add_f32_e32 v66, v157, v66
	v_add_f32_e32 v66, v159, v66
	v_add_f32_e32 v66, v155, v66
	v_add_f32_e32 v66, v156, v66
	v_add_f32_e32 v66, v152, v66
	v_add_f32_e32 v66, v154, v66
	v_mfma_f32_32x32x16_bf16 v[98:113], v[236:239], v[134:137], v[98:113]
	v_add_f32_e32 v66, v151, v66
	v_add_f32_e32 v66, v153, v66
	v_add_f32_e32 v66, v148, v66
	v_add_f32_e32 v66, v150, v66
	v_add_f32_e32 v66, v147, v66
	v_add_f32_e32 v66, v149, v66
	ds_read_b128 v[236:239], v183 offset:49152
	ds_read_b128 v[240:243], v183 offset:57344
	s_waitcnt lgkmcnt(0)
	v_mfma_f32_32x32x16_bf16 v[82:97], v[240:243], v[130:133], v[82:97]
	v_add_f32_e32 v66, v80, v66
	v_add_f32_e32 v66, v1, v66
	v_add_f32_e32 v66, v78, v66
	v_add_f32_e32 v66, v79, v66
	v_add_f32_e32 v66, v76, v66
	v_mfma_f32_32x32x16_bf16 v[98:113], v[236:239], v[130:133], v[98:113]
	v_exp_f32_e32 v228, v73
	v_add_f32_e32 v66, v77, v66
	v_exp_f32_e32 v229, v70
	v_add_f32_e32 v66, v81, v66
	ds_read_b128 v[236:239], v187 offset:49280
	ds_read_b128 v[240:243], v187 offset:57472
	s_waitcnt lgkmcnt(0)
	v_mfma_f32_32x32x16_bf16 v[82:97], v[240:243], v[126:129], v[82:97]
	v_exp_f32_e32 v230, v71
	v_add_f32_e32 v66, v146, v66
	v_exp_f32_e32 v231, v68
	v_add_f32_e32 v66, v226, v66
	v_mfma_f32_32x32x16_bf16 v[98:113], v[236:239], v[126:129], v[98:113]
	v_exp_f32_e32 v232, v69
	v_add_f32_e32 v66, v228, v66
	v_add_f32_e32 v66, v229, v66
	v_exp_f32_e32 v234, v67
	ds_read_b128 v[236:239], v185 offset:49280
	ds_read_b128 v[240:243], v185 offset:57472
	s_waitcnt lgkmcnt(0)
	v_mfma_f32_32x32x16_bf16 v[82:97], v[240:243], v[122:125], v[82:97]
	v_add_f32_e32 v66, v230, v66
	v_add_f32_e32 v66, v231, v66
	v_add_f32_e32 v66, v232, v66
	v_add_f32_e32 v66, v233, v66
	v_add_f32_e32 v224, v234, v66
	v_mov_b32_e32 v225, v224
	v_mfma_f32_32x32x16_bf16 v[98:113], v[236:239], v[122:125], v[98:113]
	v_cvt_pk_bf16_f32 v66, v160, v227
	v_cvt_pk_bf16_f32 v67, v158, v161
	v_cvt_pk_bf16_f32 v68, v157, v159
	v_cvt_pk_bf16_f32 v69, v155, v156
	v_cvt_pk_bf16_f32 v70, v152, v154
	v_cvt_pk_bf16_f32 v71, v151, v153
	ds_read_b128 v[236:239], v184 offset:49280
	ds_read_b128 v[240:243], v184 offset:57472
	s_waitcnt lgkmcnt(0)
	v_mfma_f32_32x32x16_bf16 v[82:97], v[240:243], v[118:121], v[82:97]
	v_cvt_pk_bf16_f32 v72, v148, v150
	v_cvt_pk_bf16_f32 v73, v147, v149
	v_cvt_pk_bf16_f32 v74, v80, v1
	v_cvt_pk_bf16_f32 v75, v78, v79
	v_cvt_pk_bf16_f32 v76, v76, v77
	v_cvt_pk_bf16_f32 v77, v81, v146
	v_mfma_f32_32x32x16_bf16 v[98:113], v[236:239], v[118:121], v[98:113]
	v_cvt_pk_bf16_f32 v78, v226, v228
	v_cvt_pk_bf16_f32 v79, v229, v230
	v_cvt_pk_bf16_f32 v80, v231, v232
	v_cvt_pk_bf16_f32 v81, v233, v234
	s_nop 1
	v_permlane32_swap_b32_e32 v224, v225
	ds_read_b128 v[236:239], v183 offset:49280
	ds_read_b128 v[240:243], v183 offset:57472
	s_waitcnt lgkmcnt(0)
	v_mfma_f32_32x32x16_bf16 v[82:97], v[240:243], v[114:117], v[82:97]
	v_permlane32_swap_b32_e32 v66, v68
	v_permlane32_swap_b32_e32 v67, v69
	v_permlane32_swap_b32_e32 v70, v72
	v_permlane32_swap_b32_e32 v71, v73
	v_permlane32_swap_b32_e32 v74, v76
	v_permlane32_swap_b32_e32 v75, v77
	v_mfma_f32_32x32x16_bf16 v[98:113], v[236:239], v[114:117], v[98:113]
	v_permlane32_swap_b32_e32 v78, v80
	v_permlane32_swap_b32_e32 v79, v81
	v_add_u32_e32 v227, s89, v186
	v_add_u32_e32 v146, 1, v227
	v_add_u32_e32 v148, 33, v227
	v_ashrrev_i32_e32 v147, 31, v146
	v_ashrrev_i32_e32 v149, 31, v148
	v_lshlrev_b64 v[154:155], 8, v[146:147]
	v_lshlrev_b64 v[156:157], 8, v[148:149]
	v_lshl_add_u64 v[146:147], v[176:177], 0, v[154:155]
	v_lshl_add_u64 v[150:151], v[176:177], 0, v[156:157]
	v_lshl_add_u64 v[214:215], v[212:213], 0, v[154:155]
	v_lshl_add_u64 v[210:211], v[212:213], 0, v[156:157]
	s_add_i32 m0, s32, 0x8000
	s_nop 0
	global_load_lds_dwordx4 v[214:215], off
	s_nop 3
	s_add_i32 m0, m0, 0x2000
	s_nop 0
	global_load_lds_dwordx4 v[210:211], off
	v_lshl_add_u64 v[154:155], v[178:179], 0, v[154:155]
	v_lshl_add_u64 v[158:159], v[178:179], 0, v[156:157]
	global_load_dwordx4 v[146:149], v[146:147], off
	s_nop 0
	global_load_dwordx4 v[150:153], v[150:151], off
	s_nop 0
	s_nop 0
	s_nop 0
	s_nop 0
	ds_read_b64_tr_b16 v[228:229], v181 offset:0
	ds_read_b64_tr_b16 v[230:231], v181 offset:0x800
	ds_read_b64_tr_b16 v[232:233], v181 offset:0x1000
	ds_read_b64_tr_b16 v[234:235], v181 offset:0x1800
	ds_read_b64_tr_b16 v[236:237], v181 offset:0x2000
	ds_read_b64_tr_b16 v[238:239], v181 offset:0x2800
	ds_read_b64_tr_b16 v[240:241], v181 offset:0x3000
	ds_read_b64_tr_b16 v[242:243], v181 offset:0x3800
	s_waitcnt lgkmcnt(0)
; #define LAS __attribute__((address_space(3)))
; __device__ __forceinline__ void bias_tile(f32x16& p0, f32x16& p1, const LAS float* cs) {
; #pragma unroll
;     for (int i = 0; i < 4; ++i) { const f32x4 a = *(const LAS f32x4*)(cs + 8 * i), b = *(const LAS f32x4*)(cs + 32 + 8 * i);
; #pragma unroll
;         for (int j = 0; j < 4; ++j) { p0[4 * i + j] = fmaf(p0[4 * i + j], C2, a[j]); p1[4 * i + j] = fmaf(p1[4 * i + j], C2, b[j]); } }
; }
; __device__ __forceinline__ void mask_tile(f32x16& p0, f32x16& p1, int dq) {
;     const float NEG = -__builtin_inff();
; #pragma unroll
;     for (int r = 0; r < 16; ++r) { const int c = (r & 3) + 8 * (r >> 2);
;         if (dq - c < 0) p0[r] = NEG;
;         if (dq - c - 32 < 0) p1[r] = NEG; }
; }
; template <int VB>
; __device__ __forceinline__ void pv_tile(f32x16* o, int vb0, bf16x8 pa0, bf16x8 pa1, bf16x8 pa2, bf16x8 pa3) {
;     ...
;     PV_D0(0); PV_D0(1); PV_D0(2); PV_D0(3);
	s_nop 0
	v_mfma_f32_32x32x16_bf16 v[50:65], v[66:69], v[228:231], v[50:65]
	ds_read_b64_tr_b16 v[228:229], v181 offset:0x200
	ds_read_b64_tr_b16 v[230:231], v181 offset:0xa00
	v_mfma_f32_32x32x16_bf16 v[50:65], v[70:73], v[232:235], v[50:65]
	ds_read_b64_tr_b16 v[232:233], v181 offset:0x1200
	ds_read_b64_tr_b16 v[234:235], v181 offset:0x1a00
	v_mfma_f32_32x32x16_bf16 v[50:65], v[74:77], v[236:239], v[50:65]
	ds_read_b64_tr_b16 v[236:237], v181 offset:0x2200
	ds_read_b64_tr_b16 v[238:239], v181 offset:0x2a00
	v_mfma_f32_32x32x16_bf16 v[50:65], v[78:81], v[240:243], v[50:65]
	ds_read_b64_tr_b16 v[240:241], v181 offset:0x3200
	ds_read_b64_tr_b16 v[242:243], v181 offset:0x3a00
	s_waitcnt lgkmcnt(0)
	v_mfma_f32_32x32x16_bf16 v[34:49], v[66:69], v[228:231], v[34:49]
	ds_read_b64_tr_b16 v[228:229], v181 offset:0x400
	ds_read_b64_tr_b16 v[230:231], v181 offset:0xc00
	v_mfma_f32_32x32x16_bf16 v[34:49], v[70:73], v[232:235], v[34:49]
	ds_read_b64_tr_b16 v[232:233], v181 offset:0x1400
	ds_read_b64_tr_b16 v[234:235], v181 offset:0x1c00
	v_mfma_f32_32x32x16_bf16 v[34:49], v[74:77], v[236:239], v[34:49]
	ds_read_b64_tr_b16 v[236:237], v181 offset:0x2400
	ds_read_b64_tr_b16 v[238:239], v181 offset:0x2c00
	v_mfma_f32_32x32x16_bf16 v[34:49], v[78:81], v[240:243], v[34:49]
	ds_read_b64_tr_b16 v[240:241], v181 offset:0x3400
	ds_read_b64_tr_b16 v[242:243], v181 offset:0x3c00
	s_waitcnt lgkmcnt(0)
	v_mfma_f32_32x32x16_bf16 v[18:33], v[66:69], v[228:231], v[18:33]
	ds_read_b64_tr_b16 v[228:229], v181 offset:0x600
	ds_read_b64_tr_b16 v[230:231], v181 offset:0xe00
	v_mfma_f32_32x32x16_bf16 v[18:33], v[70:73], v[232:235], v[18:33]
	ds_read_b64_tr_b16 v[232:233], v181 offset:0x1600
	ds_read_b64_tr_b16 v[234:235], v181 offset:0x1e00
	v_mfma_f32_32x32x16_bf16 v[18:33], v[74:77], v[236:239], v[18:33]
	ds_read_b64_tr_b16 v[236:237], v181 offset:0x2600
	ds_read_b64_tr_b16 v[238:239], v181 offset:0x2e00
	v_mfma_f32_32x32x16_bf16 v[18:33], v[78:81], v[240:243], v[18:33]
	ds_read_b64_tr_b16 v[240:241], v181 offset:0x3600
	ds_read_b64_tr_b16 v[242:243], v181 offset:0x3e00
	s_waitcnt lgkmcnt(0)
	v_mfma_f32_32x32x16_bf16 v[2:17], v[66:69], v[228:231], v[2:17]
	s_cmp_le_i32 s89, s80
	v_mfma_f32_32x32x16_bf16 v[2:17], v[70:73], v[232:235], v[2:17]
	v_mfma_f32_32x32x16_bf16 v[2:17], v[74:77], v[236:239], v[2:17]
	v_mfma_f32_32x32x16_bf16 v[2:17], v[78:81], v[240:243], v[2:17]
	ds_read_b128 v[228:231], v223 offset:128
	ds_read_b128 v[78:81], v223
	ds_read_b128 v[70:73], v223 offset:32
	ds_read_b128 v[232:235], v223 offset:160
	ds_read_b128 v[74:77], v223 offset:64
	ds_read_b128 v[236:239], v223 offset:192
	ds_read_b128 v[240:243], v223 offset:96
	ds_read_b128 v[244:247], v223 offset:224
	s_waitcnt lgkmcnt(6)
	v_pk_fma_f32 v[100:101], v[100:101], s[2:3], v[80:81] op_sel_hi:[1,0,1]
	s_waitcnt lgkmcnt(3)
	v_pk_fma_f32 v[68:69], v[106:107], s[2:3], v[74:75] op_sel_hi:[1,0,1]
	v_pk_fma_f32 v[74:75], v[102:103], s[2:3], v[70:71] op_sel_hi:[1,0,1]
	s_waitcnt lgkmcnt(1)
	v_pk_fma_f32 v[66:67], v[110:111], s[2:3], v[240:241] op_sel_hi:[1,0,1]
	v_pk_fma_f32 v[70:71], v[112:113], s[2:3], v[242:243] op_sel_hi:[1,0,1]
	v_pk_fma_f32 v[76:77], v[108:109], s[2:3], v[76:77] op_sel_hi:[1,0,1]
	v_pk_fma_f32 v[102:103], v[104:105], s[2:3], v[72:73] op_sel_hi:[1,0,1]
	v_pk_fma_f32 v[98:99], v[98:99], s[2:3], v[78:79] op_sel_hi:[1,0,1]
	s_waitcnt lgkmcnt(0)
	v_pk_fma_f32 v[72:73], v[94:95], s[2:3], v[244:245] op_sel_hi:[1,0,1]
	v_pk_fma_f32 v[78:79], v[90:91], s[2:3], v[236:237] op_sel_hi:[1,0,1]
	v_pk_fma_f32 v[86:87], v[86:87], s[2:3], v[232:233] op_sel_hi:[1,0,1]
	v_pk_fma_f32 v[80:81], v[96:97], s[2:3], v[246:247] op_sel_hi:[1,0,1]
	v_pk_fma_f32 v[90:91], v[92:93], s[2:3], v[238:239] op_sel_hi:[1,0,1]
	v_pk_fma_f32 v[88:89], v[88:89], s[2:3], v[234:235] op_sel_hi:[1,0,1]
	v_pk_fma_f32 v[84:85], v[84:85], s[2:3], v[230:231] op_sel_hi:[1,0,1]
	v_pk_fma_f32 v[82:83], v[82:83], s[2:3], v[228:229] op_sel_hi:[1,0,1]
	s_cbranch_scc1 .LBB0_867
	v_add_u32_e32 v1, 64, v222
	v_cmp_gt_i32_e64 s[70:71], 26, v1
	v_cmp_gt_i32_e64 s[72:73], 27, v1
	v_cmp_gt_i32_e64 s[68:69], 25, v1
	s_and_b64 s[70:71], s[72:73], s[70:71]
	v_cmp_gt_i32_e64 s[66:67], 24, v1
	s_and_b64 s[68:69], s[70:71], s[68:69]
	v_cmp_gt_i32_e64 s[64:65], 19, v1
	s_and_b64 s[66:67], s[68:69], s[66:67]
	v_cmp_gt_i32_e64 s[62:63], 18, v1
	s_and_b64 s[64:65], s[66:67], s[64:65]
	v_cmp_gt_i32_e64 s[60:61], 17, v1
	s_and_b64 s[62:63], s[64:65], s[62:63]
	v_cmp_gt_i32_e64 s[58:59], 16, v1
	s_and_b64 s[60:61], s[62:63], s[60:61]
	v_cmp_gt_i32_e64 s[56:57], 11, v1
	s_and_b64 s[58:59], s[60:61], s[58:59]
	v_cmp_gt_i32_e64 s[54:55], 10, v1
	s_and_b64 s[56:57], s[58:59], s[56:57]
	v_cmp_gt_i32_e64 s[52:53], 9, v1
	s_and_b64 s[54:55], s[56:57], s[54:55]
	v_cmp_gt_i32_e64 s[50:51], 8, v1
	s_and_b64 s[52:53], s[54:55], s[52:53]
	v_cmp_gt_i32_e64 s[48:49], 3, v1
	s_and_b64 s[50:51], s[52:53], s[50:51]
	v_cmp_gt_i32_e64 s[46:47], 2, v1
	s_and_b64 s[48:49], s[50:51], s[48:49]
	v_cmp_gt_i32_e64 s[44:45], 1, v1
	s_and_b64 s[46:47], s[48:49], s[46:47]
	v_cmp_gt_i32_e64 s[42:43], 0, v1
	s_and_b64 s[44:45], s[46:47], s[44:45]
	s_and_b64 s[42:43], s[44:45], s[42:43]
	v_cmp_gt_i32_e64 s[38:39], 58, v1
	v_cndmask_b32_e64 v98, v98, v206, s[42:43]
	v_cmp_gt_i32_e64 s[42:43], 59, v1
	v_cmp_gt_i32_e64 s[36:37], 57, v1
	s_and_b64 s[38:39], s[42:43], s[38:39]
	v_cmp_gt_i32_e64 s[34:35], 56, v1
	s_and_b64 s[36:37], s[38:39], s[36:37]
	v_cmp_gt_i32_e64 s[30:31], 51, v1
	s_and_b64 s[34:35], s[36:37], s[34:35]
	v_cmp_gt_i32_e64 s[28:29], 50, v1
	s_and_b64 s[30:31], s[34:35], s[30:31]
	v_cmp_gt_i32_e64 s[26:27], 49, v1
	s_and_b64 s[28:29], s[30:31], s[28:29]
; __device__ __forceinline__ void partialSM(f32x16& p0, f32x16& p1, float& m_reg, float& alpha) {
;     float pmax = p0[0];
; #pragma unroll
;     for (int r = 1; r < 16; ++r) pmax = fmaxf(pmax, p0[r]);
; #pragma unroll
;     for (int r = 0; r < 16; ++r) pmax = fmaxf(pmax, p1[r]);
;     { auto rr = __builtin_amdgcn_permlane32_swap(__float_as_uint(pmax), __float_as_uint(pmax), false, false);
;       pmax = fmaxf(__uint_as_float(rr[0]), __uint_as_float(rr[1])); }
;     float mn;
;     if (__builtin_expect(__all(pmax - m_reg <= THR2), 1)) { mn = m_reg; alpha = 1.f; }
;     else { mn = fmaxf(m_reg, pmax); alpha = __builtin_amdgcn_exp2f(m_reg - mn); m_reg = mn; }
	v_cmp_gt_i32_e64 s[24:25], 48, v1
	s_and_b64 s[26:27], s[28:29], s[26:27]
	v_cmp_gt_i32_e64 s[22:23], 43, v1
	s_and_b64 s[24:25], s[26:27], s[24:25]
	v_cmp_gt_i32_e64 s[20:21], 42, v1
	s_and_b64 s[22:23], s[24:25], s[22:23]
	v_cmp_gt_i32_e64 s[18:19], 41, v1
	s_and_b64 s[20:21], s[22:23], s[20:21]
	v_cmp_gt_i32_e64 s[16:17], 40, v1
	s_and_b64 s[18:19], s[20:21], s[18:19]
	v_cmp_gt_i32_e64 s[14:15], 35, v1
	s_and_b64 s[16:17], s[18:19], s[16:17]
	v_cmp_gt_i32_e64 s[12:13], 34, v1
	s_and_b64 s[14:15], s[16:17], s[14:15]
	v_cmp_gt_i32_e64 s[10:11], 33, v1
	s_and_b64 s[12:13], s[14:15], s[12:13]
	v_cmp_gt_i32_e32 vcc, 32, v1
	s_and_b64 s[10:11], s[12:13], s[10:11]
	s_and_b64 vcc, s[10:11], vcc
	v_cndmask_b32_e64 v71, v71, v206, s[72:73]
	v_cndmask_b32_e64 v70, v70, v206, s[70:71]
	v_cndmask_b32_e64 v67, v67, v206, s[68:69]
	v_cndmask_b32_e64 v66, v66, v206, s[66:67]
	v_cndmask_b32_e64 v77, v77, v206, s[64:65]
	v_cndmask_b32_e64 v76, v76, v206, s[62:63]
	v_cndmask_b32_e64 v69, v69, v206, s[60:61]
	v_cndmask_b32_e64 v68, v68, v206, s[58:59]
	v_cndmask_b32_e64 v103, v103, v206, s[56:57]
	v_cndmask_b32_e64 v102, v102, v206, s[54:55]
	v_cndmask_b32_e64 v75, v75, v206, s[52:53]
	v_cndmask_b32_e64 v74, v74, v206, s[50:51]
	v_cndmask_b32_e64 v101, v101, v206, s[48:49]
	v_cndmask_b32_e64 v100, v100, v206, s[46:47]
	v_cndmask_b32_e64 v99, v99, v206, s[44:45]
	v_cndmask_b32_e64 v81, v81, v206, s[42:43]
	v_cndmask_b32_e64 v80, v80, v206, s[38:39]
	v_cndmask_b32_e64 v73, v73, v206, s[36:37]
	v_cndmask_b32_e64 v72, v72, v206, s[34:35]
	v_cndmask_b32_e64 v91, v91, v206, s[30:31]
	v_cndmask_b32_e64 v90, v90, v206, s[28:29]
	v_cndmask_b32_e64 v79, v79, v206, s[26:27]
	v_cndmask_b32_e64 v78, v78, v206, s[24:25]
	v_cndmask_b32_e64 v89, v89, v206, s[22:23]
	v_cndmask_b32_e64 v88, v88, v206, s[20:21]
	v_cndmask_b32_e64 v87, v87, v206, s[18:19]
	v_cndmask_b32_e64 v86, v86, v206, s[16:17]
	v_cndmask_b32_e64 v85, v85, v206, s[14:15]
	v_cndmask_b32_e64 v84, v84, v206, s[12:13]
	v_cndmask_b32_e64 v83, v83, v206, s[10:11]
	v_cndmask_b32_e32 v82, v82, v206, vcc
.LBB0_867:
	v_max_f32_e32 v1, v99, v99
	v_max_f32_e32 v92, v98, v98
	v_max_f32_e32 v1, v92, v1
	v_max3_f32 v1, v1, v100, v101
	v_max3_f32 v1, v1, v74, v75
	v_max3_f32 v1, v1, v102, v103
	v_max3_f32 v1, v1, v68, v69
	v_max3_f32 v1, v1, v76, v77
	v_max3_f32 v1, v1, v66, v67
	v_max3_f32 v1, v1, v70, v71
	v_max3_f32 v1, v1, v82, v83
	v_max3_f32 v1, v1, v84, v85
	v_max3_f32 v1, v1, v86, v87
	v_max3_f32 v1, v1, v88, v89
	v_max3_f32 v1, v1, v78, v79
	v_max3_f32 v1, v1, v90, v91
	v_max3_f32 v1, v1, v72, v73
	v_max3_f32 v1, v1, v80, v81
	v_mov_b32_e32 v92, v1
	s_nop 1
	v_permlane32_swap_b32_e32 v1, v92
	v_max_f32_e32 v92, v92, v92
	v_max_f32_e32 v1, v1, v1
	v_max_f32_e32 v1, v1, v92
	v_sub_f32_e32 v92, v1, v220
	v_cmp_ge_f32_e32 vcc, s84, v92
	v_max_f32_e32 v92, v220, v220
	v_max_f32_e32 v1, v92, v1
	v_sub_f32_e32 v92, v220, v1
	v_exp_f32_e32 v92, v92
	s_cmp_eq_u64 vcc, exec
	s_cselect_b64 s[10:11], -1, 0
	s_barrier
	s_waitcnt vmcnt(0)
	v_cndmask_b32_e64 v226, v92, 1.0, s[10:11]
	v_cmp_gt_f32_e32 vcc, 1.0, v226
	s_waitcnt vmcnt(1)
	ds_write_b128 v188, v[146:149]
	s_waitcnt vmcnt(0)
	ds_write_b128 v189, v[150:153]
	s_waitcnt vmcnt(1)
	s_nop 0
	s_waitcnt vmcnt(0)
	s_nop 0
	s_waitcnt lgkmcnt(0)
	s_cbranch_vccz .LBB0_871
	s_and_saveexec_b64 s[12:13], s[8:9]
	ds_write_b32 v221, v226 offset:128
	s_or_b64 exec, exec, s[12:13]
	s_waitcnt lgkmcnt(0)
	ds_read_b128 v[92:95], v218 offset:224
	ds_read_b128 v[104:107], v218 offset:192
	ds_read_b128 v[108:111], v218 offset:160
	ds_read_b128 v[228:231], v218 offset:128
	s_waitcnt lgkmcnt(3)
	v_pk_mul_f32 v[64:65], v[64:65], v[94:95]
	s_waitcnt lgkmcnt(2)
	v_pk_mul_f32 v[60:61], v[60:61], v[106:107]
	s_waitcnt lgkmcnt(1)
	v_pk_mul_f32 v[56:57], v[56:57], v[110:111]
	s_waitcnt lgkmcnt(0)
	v_pk_mul_f32 v[52:53], v[52:53], v[230:231]
	v_pk_mul_f32 v[62:63], v[62:63], v[92:93]
	v_pk_mul_f32 v[58:59], v[58:59], v[104:105]
	v_pk_mul_f32 v[54:55], v[54:55], v[108:109]
	v_pk_mul_f32 v[50:51], v[50:51], v[228:229]
	v_pk_mul_f32 v[48:49], v[48:49], v[94:95]
	v_pk_mul_f32 v[44:45], v[44:45], v[106:107]
	v_pk_mul_f32 v[40:41], v[40:41], v[110:111]
	v_pk_mul_f32 v[36:37], v[36:37], v[230:231]
	v_pk_mul_f32 v[46:47], v[46:47], v[92:93]
	v_pk_mul_f32 v[42:43], v[42:43], v[104:105]
	v_pk_mul_f32 v[38:39], v[38:39], v[108:109]
	v_pk_mul_f32 v[34:35], v[34:35], v[228:229]
	v_pk_mul_f32 v[32:33], v[32:33], v[94:95]
	v_pk_mul_f32 v[28:29], v[28:29], v[106:107]
	v_pk_mul_f32 v[24:25], v[24:25], v[110:111]
	v_pk_mul_f32 v[20:21], v[20:21], v[230:231]
	v_pk_mul_f32 v[30:31], v[30:31], v[92:93]
	v_pk_mul_f32 v[26:27], v[26:27], v[104:105]
	v_pk_mul_f32 v[22:23], v[22:23], v[108:109]
	v_pk_mul_f32 v[18:19], v[18:19], v[228:229]
	v_pk_mul_f32 v[16:17], v[16:17], v[94:95]
	v_pk_mul_f32 v[12:13], v[12:13], v[106:107]
	v_pk_mul_f32 v[8:9], v[8:9], v[110:111]
	v_pk_mul_f32 v[4:5], v[4:5], v[230:231]
	v_pk_mul_f32 v[14:15], v[14:15], v[92:93]
	v_pk_mul_f32 v[10:11], v[10:11], v[104:105]
	v_pk_mul_f32 v[6:7], v[6:7], v[108:109]
	v_pk_mul_f32 v[2:3], v[2:3], v[228:229]
; #define LAS __attribute__((address_space(3)))
; __device__ __forceinline__ void partialSM(f32x16& p0, f32x16& p1, float& m_reg, float& alpha) {
;     ...
; #pragma unroll
;     for (int r = 0; r < 16; ++r) p0[r] = p0[r] - mn;
; #pragma unroll
;     for (int r = 0; r < 16; ++r) p1[r] = p1[r] - mn;
; #pragma unroll
;     for (int r = 0; r < 16; ++r) p0[r] = __builtin_amdgcn_exp2f(p0[r]);
; }
; __device__ __forceinline__ void finishSM(f32x16& p0, f32x16& p1, float alpha, float& l_reg, bf16x8& pa0, bf16x8& pa1, bf16x8& pa2, bf16x8& pa3) {
; #pragma unroll
;     for (int r = 0; r < 16; ++r) p1[r] = __builtin_amdgcn_exp2f(p1[r]);
;     float ps = 0;
; #pragma unroll
;     for (int r = 0; r < 16; ++r) ps += p0[r];
; #pragma unroll
;     for (int r = 0; r < 16; ++r) ps += p1[r];
;     { auto rr = __builtin_amdgcn_permlane32_swap(__float_as_uint(ps), __float_as_uint(ps), false, false);
;       ps = __uint_as_float(rr[0]) + __uint_as_float(rr[1]); }
;     l_reg = l_reg * alpha + ps;
;     ...
;     PK4(p0, 0, pa0); PK4(p0, 8, pa1); PK4(p1, 0, pa2); PK4(p1, 8, pa3);
; template <int KB>
; __device__ __forceinline__ void qkt(f32x16& p0, f32x16& p1, lptr K_lds, int r32, int hi, const bf16x8* qr) {
;     p0 = f32x16{}; p1 = f32x16{};
;     lptr kb[4];
; #pragma unroll
;     for (int dd = 0; dd < 4; ++dd) kb[dd] = K_lds + KB * SHM_K + KSWZ(r32, (dd * 16 + hi * 8) * 2);
; #pragma unroll
;     for (int d0 = 0; d0 < 8; ++d0) { lptr a = kb[d0 & 3] + (d0 >> 2) * 128;
;         bf16x8 b0 = *reinterpret_cast<const LAS bf16x8*>(a);
;         bf16x8 b1 = *reinterpret_cast<const LAS bf16x8*>(a + 32 * 256);
;         p0 = __builtin_amdgcn_mfma_f32_32x32x16_bf16(b0, qr[d0], p0, 0, 0, 0);
;         p1 = __builtin_amdgcn_mfma_f32_32x32x16_bf16(b1, qr[d0], p1, 0, 0, 0); }
; }
.LBB0_871:
	v_cndmask_b32_e64 v1, v1, v220, s[10:11]
	v_sub_f32_e32 v92, v98, v1
	v_sub_f32_e32 v93, v99, v1
	v_sub_f32_e32 v94, v100, v1
	v_sub_f32_e32 v95, v101, v1
	v_sub_f32_e32 v74, v74, v1
	v_sub_f32_e32 v75, v75, v1
	v_sub_f32_e32 v96, v102, v1
	v_sub_f32_e32 v97, v103, v1
	v_sub_f32_e32 v68, v68, v1
	v_sub_f32_e32 v69, v69, v1
	v_sub_f32_e32 v76, v76, v1
	v_sub_f32_e32 v77, v77, v1
	v_sub_f32_e32 v66, v66, v1
	v_sub_f32_e32 v67, v67, v1
	v_sub_f32_e32 v70, v70, v1
	v_sub_f32_e32 v71, v71, v1
	v_exp_f32_e32 v98, v92
	v_exp_f32_e32 v113, v93
	v_exp_f32_e32 v99, v94
	v_exp_f32_e32 v112, v95
	v_exp_f32_e32 v100, v74
	v_exp_f32_e32 v111, v75
	v_exp_f32_e32 v101, v96
	v_exp_f32_e32 v110, v97
	v_exp_f32_e32 v102, v68
	v_exp_f32_e32 v109, v69
	v_exp_f32_e32 v103, v76
	v_exp_f32_e32 v108, v77
	v_exp_f32_e32 v104, v66
	v_exp_f32_e32 v107, v67
	v_exp_f32_e32 v105, v70
	v_exp_f32_e32 v106, v71
	v_sub_f32_e32 v220, v82, v1
	v_sub_f32_e32 v236, v83, v1
	v_sub_f32_e32 v237, v84, v1
	v_sub_f32_e32 v238, v85, v1
	v_sub_f32_e32 v239, v86, v1
	v_sub_f32_e32 v240, v87, v1
	v_sub_f32_e32 v241, v88, v1
	v_sub_f32_e32 v242, v89, v1
	v_sub_f32_e32 v243, v78, v1
	v_sub_f32_e32 v244, v79, v1
	v_sub_f32_e32 v245, v90, v1
	v_sub_f32_e32 v246, v91, v1
	v_sub_f32_e32 v247, v72, v1
	v_sub_f32_e32 v248, v73, v1
	v_sub_f32_e32 v249, v80, v1
	v_sub_f32_e32 v250, v81, v1
	s_waitcnt lgkmcnt(0)
	s_waitcnt vmcnt(0)
	s_barrier
	ds_read_b128 v[66:69], v187 offset:32768
	ds_read_b128 v[70:73], v187 offset:40960
	ds_read_b128 v[146:149], v185 offset:32768
	ds_read_b128 v[150:153], v185 offset:40960
	s_waitcnt lgkmcnt(3)
	v_mfma_f32_32x32x16_bf16 v[82:97], v[66:69], v[142:145], 0
	v_exp_f32_e32 v220, v220
	v_add_f32_e32 v228, 0, v98
	v_add_f32_e32 v228, v113, v228
	v_add_f32_e32 v228, v99, v228
	v_add_f32_e32 v228, v112, v228
	s_waitcnt lgkmcnt(2)
	v_mfma_f32_32x32x16_bf16 v[66:81], v[70:73], v[142:145], 0
	v_add_f32_e32 v228, v100, v228
	v_add_f32_e32 v228, v111, v228
	v_add_f32_e32 v228, v101, v228
	v_add_f32_e32 v228, v110, v228
	v_add_f32_e32 v228, v102, v228
	v_add_f32_e32 v228, v109, v228
	s_waitcnt lgkmcnt(1)
	v_mfma_f32_32x32x16_bf16 v[82:97], v[146:149], v[138:141], v[82:97]
	v_add_f32_e32 v228, v103, v228
	v_add_f32_e32 v228, v108, v228
	v_add_f32_e32 v228, v104, v228
	v_exp_f32_e32 v230, v236
	v_add_f32_e32 v228, v107, v228
	s_waitcnt lgkmcnt(0)
	v_mfma_f32_32x32x16_bf16 v[66:81], v[150:153], v[138:141], v[66:81]
	v_exp_f32_e32 v231, v237
	v_add_f32_e32 v228, v105, v228
	v_exp_f32_e32 v232, v238
	v_add_f32_e32 v228, v106, v228
	ds_read_b128 v[146:149], v184 offset:32768
	ds_read_b128 v[150:153], v184 offset:40960
	s_waitcnt lgkmcnt(1)
	v_mfma_f32_32x32x16_bf16 v[82:97], v[146:149], v[134:137], v[82:97]
	v_exp_f32_e32 v233, v239
	v_add_f32_e32 v228, v220, v228
	v_exp_f32_e32 v234, v240
	v_add_f32_e32 v228, v230, v228
	s_waitcnt lgkmcnt(0)
	v_mfma_f32_32x32x16_bf16 v[66:81], v[150:153], v[134:137], v[66:81]
	v_exp_f32_e32 v235, v241
	v_add_f32_e32 v228, v231, v228
	v_exp_f32_e32 v236, v242
	v_add_f32_e32 v228, v232, v228
	ds_read_b128 v[146:149], v183 offset:32768
	ds_read_b128 v[150:153], v183 offset:40960
	s_waitcnt lgkmcnt(1)
	v_mfma_f32_32x32x16_bf16 v[82:97], v[146:149], v[130:133], v[82:97]
	v_exp_f32_e32 v237, v243
	v_add_f32_e32 v228, v233, v228
	v_exp_f32_e32 v238, v244
	v_add_f32_e32 v228, v234, v228
	s_waitcnt lgkmcnt(0)
	v_mfma_f32_32x32x16_bf16 v[66:81], v[150:153], v[130:133], v[66:81]
	v_exp_f32_e32 v239, v245
	v_add_f32_e32 v228, v235, v228
	v_exp_f32_e32 v240, v246
	v_add_f32_e32 v228, v236, v228
	ds_read_b128 v[146:149], v187 offset:32896
	ds_read_b128 v[150:153], v187 offset:41088
	s_waitcnt lgkmcnt(1)
	v_mfma_f32_32x32x16_bf16 v[82:97], v[146:149], v[126:129], v[82:97]
	v_exp_f32_e32 v241, v247
	v_add_f32_e32 v228, v237, v228
	v_exp_f32_e32 v242, v248
	v_add_f32_e32 v228, v238, v228
	s_waitcnt lgkmcnt(0)
	v_mfma_f32_32x32x16_bf16 v[66:81], v[150:153], v[126:129], v[66:81]
	v_exp_f32_e32 v243, v249
	v_add_f32_e32 v228, v239, v228
	v_exp_f32_e32 v244, v250
	v_add_f32_e32 v228, v240, v228
	ds_read_b128 v[146:149], v185 offset:32896
	ds_read_b128 v[150:153], v185 offset:41088
	s_waitcnt lgkmcnt(1)
	v_mfma_f32_32x32x16_bf16 v[82:97], v[146:149], v[122:125], v[82:97]
	v_add_f32_e32 v228, v241, v228
	v_add_f32_e32 v228, v242, v228
	v_add_f32_e32 v228, v243, v228
	v_add_f32_e32 v228, v244, v228
	v_mov_b32_e32 v229, v228
	v_cvt_pk_bf16_f32 v98, v98, v113
	s_waitcnt lgkmcnt(0)
	v_mfma_f32_32x32x16_bf16 v[66:81], v[150:153], v[122:125], v[66:81]
	v_cvt_pk_bf16_f32 v99, v99, v112
	v_cvt_pk_bf16_f32 v100, v100, v111
	v_cvt_pk_bf16_f32 v101, v101, v110
	v_cvt_pk_bf16_f32 v102, v102, v109
	v_cvt_pk_bf16_f32 v103, v103, v108
	v_cvt_pk_bf16_f32 v104, v104, v107
	ds_read_b128 v[146:149], v184 offset:32896
	ds_read_b128 v[150:153], v184 offset:41088
	s_waitcnt lgkmcnt(1)
	v_mfma_f32_32x32x16_bf16 v[82:97], v[146:149], v[118:121], v[82:97]
	v_cvt_pk_bf16_f32 v105, v105, v106
	v_cvt_pk_bf16_f32 v106, v220, v230
	v_cvt_pk_bf16_f32 v107, v231, v232
	v_cvt_pk_bf16_f32 v108, v233, v234
	v_cvt_pk_bf16_f32 v109, v235, v236
	v_cvt_pk_bf16_f32 v110, v237, v238
	s_waitcnt lgkmcnt(0)
	v_mfma_f32_32x32x16_bf16 v[66:81], v[150:153], v[118:121], v[66:81]
	v_cvt_pk_bf16_f32 v111, v239, v240
	v_cvt_pk_bf16_f32 v112, v241, v242
	v_cvt_pk_bf16_f32 v113, v243, v244
	s_nop 1
	v_permlane32_swap_b32_e32 v228, v229
	v_permlane32_swap_b32_e32 v98, v100
	ds_read_b128 v[146:149], v183 offset:32896
	ds_read_b128 v[150:153], v183 offset:41088
	s_waitcnt lgkmcnt(1)
	v_mfma_f32_32x32x16_bf16 v[82:97], v[146:149], v[114:117], v[82:97]
	v_permlane32_swap_b32_e32 v99, v101
	v_permlane32_swap_b32_e32 v102, v104
	v_permlane32_swap_b32_e32 v103, v105
	v_permlane32_swap_b32_e32 v106, v108
	v_permlane32_swap_b32_e32 v107, v109
	v_permlane32_swap_b32_e32 v110, v112
	s_waitcnt lgkmcnt(0)
	v_mfma_f32_32x32x16_bf16 v[66:81], v[150:153], v[114:117], v[66:81]
	v_permlane32_swap_b32_e32 v111, v113
	s_add_i32 s10, s88, 1
	s_cmp_lt_i32 s10, s81
	s_cselect_b64 s[40:41], -1, 0
	s_cmp_ge_i32 s10, s81
	s_cbranch_scc1 .LBB0_873
	v_add_u32_e32 v146, 0x41, v227
	v_add_u32_e32 v148, 0x61, v227
	v_ashrrev_i32_e32 v147, 31, v146
	v_ashrrev_i32_e32 v149, 31, v148
	v_lshlrev_b64 v[154:155], 8, v[146:147]
	v_lshlrev_b64 v[156:157], 8, v[148:149]
	v_lshl_add_u64 v[146:147], v[176:177], 0, v[154:155]
	v_lshl_add_u64 v[150:151], v[176:177], 0, v[156:157]
	v_lshl_add_u64 v[214:215], v[212:213], 0, v[154:155]
	v_lshl_add_u64 v[210:211], v[212:213], 0, v[156:157]
	s_add_i32 m0, s32, 0xc000
	s_nop 0
	global_load_lds_dwordx4 v[214:215], off
	s_nop 3
	s_add_i32 m0, m0, 0x2000
	s_nop 0
	global_load_lds_dwordx4 v[210:211], off
	v_lshl_add_u64 v[154:155], v[178:179], 0, v[154:155]
	v_lshl_add_u64 v[158:159], v[178:179], 0, v[156:157]
	global_load_dwordx4 v[146:149], v[146:147], off
	s_nop 0
	global_load_dwordx4 v[150:153], v[150:151], off
	s_nop 0
	s_nop 0
	s_nop 0
	s_nop 0

; __device__ __forceinline__ void partialSM(f32x16& p0, f32x16& p1, float& m_reg, float& alpha) {
;     float pmax = p0[0];
; #pragma unroll
;     for (int r = 1; r < 16; ++r) pmax = fmaxf(pmax, p0[r]);
; #pragma unroll
;     for (int r = 0; r < 16; ++r) pmax = fmaxf(pmax, p1[r]);
;     { auto rr = __builtin_amdgcn_permlane32_swap(__float_as_uint(pmax), __float_as_uint(pmax), false, false);
;       pmax = fmaxf(__uint_as_float(rr[0]), __uint_as_float(rr[1])); }
;     float mn;
;     if (__builtin_expect(__all(pmax - m_reg <= THR2), 1)) { mn = m_reg; alpha = 1.f; }
;     else { mn = fmaxf(m_reg, pmax); alpha = __builtin_amdgcn_exp2f(m_reg - mn); m_reg = mn; }
.LBB0_875:
	v_max_f32_e32 v66, v103, v103
	v_max_f32_e32 v67, v102, v102
	v_max_f32_e32 v66, v67, v66
	v_max3_f32 v66, v66, v98, v99
	v_max3_f32 v66, v66, v100, v101
	v_max3_f32 v66, v66, v88, v89
	v_max3_f32 v66, v66, v90, v91
	v_max3_f32 v66, v66, v92, v93
	v_max3_f32 v66, v66, v84, v85
	v_max3_f32 v66, v66, v96, v97
	v_max3_f32 v66, v66, v80, v81
	v_max3_f32 v66, v66, v94, v95
	v_max3_f32 v66, v66, v78, v79
	v_max3_f32 v66, v66, v86, v87
	v_max3_f32 v66, v66, v72, v73
	v_max3_f32 v66, v66, v76, v77
	v_max3_f32 v66, v66, v68, v69
	v_max3_f32 v66, v66, v82, v83
	v_mov_b32_e32 v67, v66
	s_nop 1
	v_permlane32_swap_b32_e32 v66, v67
	v_max_f32_e32 v67, v67, v67
	v_max_f32_e32 v66, v66, v66
	v_max_f32_e32 v66, v66, v67
	v_sub_f32_e32 v67, v66, v1
	v_cmp_ge_f32_e32 vcc, s84, v67
	s_cmp_eq_u64 vcc, exec
	s_cselect_b64 s[10:11], -1, 0
	s_andn2_b64 vcc, exec, s[40:41]
	s_barrier
	s_cbranch_vccnz .LBB0_877
	s_waitcnt vmcnt(0)
	s_waitcnt vmcnt(1)
	ds_write_b128 v188, v[146:149] offset:16384
	s_waitcnt vmcnt(0)
	ds_write_b128 v189, v[150:153] offset:16384
	s_waitcnt vmcnt(1)
	s_nop 0
	s_waitcnt vmcnt(0)
	s_nop 0
	s_waitcnt lgkmcnt(0)

; __device__ __forceinline__ void block(const BlockRef& cur, const int j0, const int NT, const int split, const SplitRef sp, lptr lds, int tid) {
;     ...
;     for (int t = 1; t + 1 < NT; t += 2) {
;         HALF_STEP(pB0, pB1, alB, pA0, pA1, alA, t, 1, 0, 0);
;         HALF_STEP(pA0, pA1, alA, pB0, pB1, alB, t + 1, 0, 1, 1);
;     }
.LBB0_881:
	v_cndmask_b32_e64 v220, v66, v1, s[10:11]
	v_sub_f32_e32 v1, v102, v220
	v_sub_f32_e32 v66, v103, v220
	v_sub_f32_e32 v67, v98, v220
	v_sub_f32_e32 v70, v99, v220
	v_sub_f32_e32 v71, v100, v220
	v_sub_f32_e32 v74, v101, v220
	v_sub_f32_e32 v75, v88, v220
	v_sub_f32_e32 v88, v89, v220
	v_sub_f32_e32 v89, v90, v220
	v_sub_f32_e32 v90, v91, v220
	v_sub_f32_e32 v91, v92, v220
	v_sub_f32_e32 v92, v93, v220
	v_sub_f32_e32 v84, v84, v220
	v_sub_f32_e32 v85, v85, v220
	v_sub_f32_e32 v93, v96, v220
	v_sub_f32_e32 v96, v97, v220
	s_waitcnt vmcnt(0)
	v_exp_f32_e32 v160, v1
	v_exp_f32_e32 v227, v66
	v_exp_f32_e32 v158, v67
	v_exp_f32_e32 v161, v70
	v_exp_f32_e32 v157, v71
	v_exp_f32_e32 v159, v74
	v_exp_f32_e32 v155, v75
	v_exp_f32_e32 v156, v88
	v_exp_f32_e32 v152, v89
	v_exp_f32_e32 v154, v90
	v_exp_f32_e32 v151, v91
	v_exp_f32_e32 v153, v92
	v_exp_f32_e32 v148, v84
	v_exp_f32_e32 v150, v85
	v_exp_f32_e32 v147, v93
	v_exp_f32_e32 v149, v96
	v_sub_f32_e32 v1, v81, v220
	v_add_f32_e32 v81, v224, v225
	v_fmac_f32_e32 v81, v191, v162
	v_add_f32_e32 v162, v228, v229
	s_addk_i32 s89, 0x80
	s_add_i32 s88, s88, 2
	v_sub_f32_e32 v67, v83, v220
	v_sub_f32_e32 v66, v82, v220
	v_sub_f32_e32 v69, v69, v220
	v_sub_f32_e32 v68, v68, v220
	v_sub_f32_e32 v71, v77, v220
	v_sub_f32_e32 v70, v76, v220
	v_sub_f32_e32 v73, v73, v220
	v_sub_f32_e32 v72, v72, v220
	v_sub_f32_e32 v75, v87, v220
	v_sub_f32_e32 v74, v86, v220
	v_sub_f32_e32 v77, v79, v220
	v_sub_f32_e32 v76, v78, v220
	v_sub_f32_e32 v79, v95, v220
	v_sub_f32_e32 v78, v94, v220
	v_fmac_f32_e32 v162, v81, v226
	v_add_u32_e32 v222, 0xffffff80, v222
	v_add_u32_e32 v223, 0x200, v223
	s_cmp_ge_i32 s88, s81
	v_sub_f32_e32 v80, v80, v220
	s_waitcnt lgkmcnt(0)
	s_waitcnt vmcnt(0)
	s_barrier
	s_cbranch_scc1 .LBB0_884
	v_mov_b32_e32 v191, v146
	s_branch .LBB0_865
